# retention scan: state-update MFMA section rescheduled (36 LDS fragment reads issued in consumption order, 11-15 in flight, counted lgkm waits instead of ~14 full drains per step)
# baseline (speedup 1.0000x reference)
.LBB0_381:
	s_waitcnt lgkmcnt(0)
	s_barrier
	ds_read_b128 v[240:243], v166 offset:34816
	ds_read_b128 v[244:247], v166 offset:34880
	ds_read_b128 v[248:251], v166 offset:34944
	ds_read_b128 v[252:255], v166 offset:35008
	ds_read_b128 v[168:171], v167
	ds_read_b128 v[172:175], v167 offset:4352
	ds_read_b128 v[176:179], v167 offset:8704
	ds_read_b128 v[180:183], v167 offset:13056
	ds_read_b128 v[184:187], v167 offset:17408
	ds_read_b128 v[188:191], v167 offset:21760
	ds_read_b128 v[192:195], v167 offset:26112
	ds_read_b128 v[196:199], v167 offset:30464
	ds_read_b128 v[200:203], v167 offset:64
	ds_read_b128 v[204:207], v167 offset:4416
	ds_read_b128 v[208:211], v167 offset:8768
	v_pk_mul_f32 v[126:127], v[142:143], v[126:127]
	v_pk_mul_f32 v[124:125], v[140:141], v[124:125]
	v_pk_mul_f32 v[122:123], v[142:143], v[122:123]
	v_pk_mul_f32 v[120:121], v[140:141], v[120:121]
	v_pk_mul_f32 v[118:119], v[142:143], v[118:119]
	v_pk_mul_f32 v[116:117], v[140:141], v[116:117]
	v_pk_mul_f32 v[114:115], v[142:143], v[114:115]
	v_pk_mul_f32 v[112:113], v[140:141], v[112:113]
	v_pk_mul_f32 v[110:111], v[142:143], v[110:111]
	v_pk_mul_f32 v[108:109], v[140:141], v[108:109]
	v_pk_mul_f32 v[106:107], v[142:143], v[106:107]
	v_pk_mul_f32 v[104:105], v[140:141], v[104:105]
	v_pk_mul_f32 v[102:103], v[142:143], v[102:103]
	v_pk_mul_f32 v[100:101], v[140:141], v[100:101]
	v_pk_mul_f32 v[98:99], v[142:143], v[98:99]
	v_pk_mul_f32 v[96:97], v[140:141], v[96:97]
	s_waitcnt lgkmcnt(10)
	v_mfma_f32_16x16x32_bf16 v[124:127], v[168:171], v[240:243], v[124:127]
	ds_read_b128 v[168:171], v167 offset:13120
	s_waitcnt lgkmcnt(10)
	v_mfma_f32_16x16x32_bf16 v[120:123], v[172:175], v[240:243], v[120:123]
	ds_read_b128 v[172:175], v167 offset:17472
	s_waitcnt lgkmcnt(10)
	v_mfma_f32_16x16x32_bf16 v[116:119], v[176:179], v[240:243], v[116:119]
	ds_read_b128 v[176:179], v167 offset:21824
	s_waitcnt lgkmcnt(10)
	v_mfma_f32_16x16x32_bf16 v[112:115], v[180:183], v[240:243], v[112:115]
	ds_read_b128 v[180:183], v167 offset:26176
	s_waitcnt lgkmcnt(10)
	v_mfma_f32_16x16x32_bf16 v[108:111], v[184:187], v[240:243], v[108:111]
	ds_read_b128 v[184:187], v167 offset:30528
	s_waitcnt lgkmcnt(10)
	v_mfma_f32_16x16x32_bf16 v[104:107], v[188:191], v[240:243], v[104:107]
	ds_read_b128 v[188:191], v167 offset:128
	s_waitcnt lgkmcnt(10)
	v_mfma_f32_16x16x32_bf16 v[100:103], v[192:195], v[240:243], v[100:103]
	ds_read_b128 v[192:195], v167 offset:4480
	s_waitcnt lgkmcnt(10)
	v_mfma_f32_16x16x32_bf16 v[96:99], v[196:199], v[240:243], v[96:99]
	ds_read_b128 v[196:199], v167 offset:8832
	s_waitcnt lgkmcnt(10)
	v_mfma_f32_16x16x32_bf16 v[124:127], v[200:203], v[244:247], v[124:127]
	ds_read_b128 v[200:203], v167 offset:13184
	s_waitcnt lgkmcnt(10)
	v_mfma_f32_16x16x32_bf16 v[120:123], v[204:207], v[244:247], v[120:123]
	ds_read_b128 v[204:207], v167 offset:17536
	s_waitcnt lgkmcnt(10)
	v_mfma_f32_16x16x32_bf16 v[116:119], v[208:211], v[244:247], v[116:119]
	ds_read_b128 v[208:211], v167 offset:21888
	s_waitcnt lgkmcnt(10)
	v_mfma_f32_16x16x32_bf16 v[112:115], v[168:171], v[244:247], v[112:115]
	ds_read_b128 v[168:171], v167 offset:26240
	s_waitcnt lgkmcnt(10)
	v_mfma_f32_16x16x32_bf16 v[108:111], v[172:175], v[244:247], v[108:111]
	ds_read_b128 v[172:175], v167 offset:30592
	s_waitcnt lgkmcnt(10)
	v_mfma_f32_16x16x32_bf16 v[104:107], v[176:179], v[244:247], v[104:107]
	ds_read_b128 v[176:179], v167 offset:192
	s_waitcnt lgkmcnt(10)
	v_mfma_f32_16x16x32_bf16 v[100:103], v[180:183], v[244:247], v[100:103]
	ds_read_b128 v[180:183], v167 offset:4544
	s_waitcnt lgkmcnt(10)
	v_mfma_f32_16x16x32_bf16 v[96:99], v[184:187], v[244:247], v[96:99]
	ds_read_b128 v[184:187], v167 offset:26304
	s_waitcnt lgkmcnt(10)
	v_mfma_f32_16x16x32_bf16 v[124:127], v[188:191], v[248:251], v[124:127]
	ds_read_b128 v[188:191], v167 offset:21952
	s_waitcnt lgkmcnt(10)
	v_mfma_f32_16x16x32_bf16 v[120:123], v[192:195], v[248:251], v[120:123]
	ds_read_b128 v[192:195], v167 offset:17600
	s_waitcnt lgkmcnt(10)
	v_mfma_f32_16x16x32_bf16 v[116:119], v[196:199], v[248:251], v[116:119]
	ds_read_b128 v[196:199], v167 offset:13248
	s_waitcnt lgkmcnt(10)
	v_mfma_f32_16x16x32_bf16 v[112:115], v[200:203], v[248:251], v[112:115]
	ds_read_b128 v[200:203], v167 offset:8896
	s_waitcnt lgkmcnt(10)
	v_mfma_f32_16x16x32_bf16 v[108:111], v[204:207], v[248:251], v[108:111]
	ds_read_b128 v[204:207], v167 offset:30656
	s_waitcnt lgkmcnt(10)
	v_mfma_f32_16x16x32_bf16 v[104:107], v[208:211], v[248:251], v[104:107]
	s_waitcnt lgkmcnt(9)
	v_mfma_f32_16x16x32_bf16 v[100:103], v[168:171], v[248:251], v[100:103]
	s_waitcnt lgkmcnt(8)
	v_mfma_f32_16x16x32_bf16 v[212:215], v[172:175], v[248:251], v[96:99]
	s_waitcnt lgkmcnt(7)
	v_mfma_f32_16x16x32_bf16 v[124:127], v[176:179], v[252:255], v[124:127]
	s_waitcnt lgkmcnt(6)
	v_mfma_f32_16x16x32_bf16 v[120:123], v[180:183], v[252:255], v[120:123]
	s_waitcnt lgkmcnt(5)
	v_mfma_f32_16x16x32_bf16 v[96:99], v[184:187], v[252:255], v[100:103]
	s_waitcnt lgkmcnt(4)
	v_mfma_f32_16x16x32_bf16 v[100:103], v[188:191], v[252:255], v[104:107]
	s_waitcnt lgkmcnt(3)
	v_mfma_f32_16x16x32_bf16 v[104:107], v[192:195], v[252:255], v[108:111]
	s_waitcnt lgkmcnt(2)
	v_mfma_f32_16x16x32_bf16 v[108:111], v[196:199], v[252:255], v[112:115]
	s_waitcnt lgkmcnt(1)
	v_mfma_f32_16x16x32_bf16 v[112:115], v[200:203], v[252:255], v[116:119]
	s_waitcnt lgkmcnt(0)
	v_mfma_f32_16x16x32_bf16 v[116:119], v[204:207], v[252:255], v[212:215]
	s_add_i32 s23, s23, 1
	s_add_i32 s3, s3, 2
	s_add_i32 s13, s13, -2
	s_cmp_lg_u32 s3, 34
	s_cbranch_scc0 .LBB0_406

.LBB0_393:
	s_waitcnt lgkmcnt(0)
	s_barrier
	ds_read_b128 v[240:243], v166 offset:34816
	ds_read_b128 v[244:247], v166 offset:34880
	ds_read_b128 v[248:251], v166 offset:34944
	ds_read_b128 v[252:255], v166 offset:35008
	ds_read_b128 v[168:171], v167
	ds_read_b128 v[172:175], v167 offset:4352
	ds_read_b128 v[176:179], v167 offset:8704
	ds_read_b128 v[180:183], v167 offset:13056
	ds_read_b128 v[184:187], v167 offset:17408
	ds_read_b128 v[188:191], v167 offset:21760
	ds_read_b128 v[192:195], v167 offset:26112
	ds_read_b128 v[196:199], v167 offset:30464
	ds_read_b128 v[200:203], v167 offset:64
	ds_read_b128 v[204:207], v167 offset:4416
	ds_read_b128 v[208:211], v167 offset:8768
	v_pk_mul_f32 v[126:127], v[142:143], v[126:127]
	v_pk_mul_f32 v[124:125], v[140:141], v[124:125]
	v_pk_mul_f32 v[122:123], v[142:143], v[122:123]
	v_pk_mul_f32 v[120:121], v[140:141], v[120:121]
	v_pk_mul_f32 v[114:115], v[142:143], v[114:115]
	v_pk_mul_f32 v[112:113], v[140:141], v[112:113]
	v_pk_mul_f32 v[110:111], v[142:143], v[110:111]
	v_pk_mul_f32 v[108:109], v[140:141], v[108:109]
	v_pk_mul_f32 v[106:107], v[142:143], v[106:107]
	v_pk_mul_f32 v[104:105], v[140:141], v[104:105]
	v_pk_mul_f32 v[102:103], v[142:143], v[102:103]
	v_pk_mul_f32 v[100:101], v[140:141], v[100:101]
	v_pk_mul_f32 v[98:99], v[142:143], v[98:99]
	v_pk_mul_f32 v[96:97], v[140:141], v[96:97]
	v_pk_mul_f32 v[118:119], v[142:143], v[118:119]
	v_pk_mul_f32 v[116:117], v[140:141], v[116:117]
	s_waitcnt lgkmcnt(10)
	v_mfma_f32_16x16x32_bf16 v[124:127], v[168:171], v[240:243], v[124:127]
	ds_read_b128 v[168:171], v167 offset:13120
	s_waitcnt lgkmcnt(10)
	v_mfma_f32_16x16x32_bf16 v[120:123], v[172:175], v[240:243], v[120:123]
	ds_read_b128 v[172:175], v167 offset:17472
	s_waitcnt lgkmcnt(10)
	v_mfma_f32_16x16x32_bf16 v[112:115], v[176:179], v[240:243], v[112:115]
	ds_read_b128 v[176:179], v167 offset:21824
	s_waitcnt lgkmcnt(10)
	v_mfma_f32_16x16x32_bf16 v[108:111], v[180:183], v[240:243], v[108:111]
	ds_read_b128 v[180:183], v167 offset:26176
	s_waitcnt lgkmcnt(10)
	v_mfma_f32_16x16x32_bf16 v[104:107], v[184:187], v[240:243], v[104:107]
	ds_read_b128 v[184:187], v167 offset:30528
	s_waitcnt lgkmcnt(10)
	v_mfma_f32_16x16x32_bf16 v[100:103], v[188:191], v[240:243], v[100:103]
	ds_read_b128 v[188:191], v167 offset:128
	s_waitcnt lgkmcnt(10)
	v_mfma_f32_16x16x32_bf16 v[96:99], v[192:195], v[240:243], v[96:99]
	ds_read_b128 v[192:195], v167 offset:4480
	s_waitcnt lgkmcnt(10)
	v_mfma_f32_16x16x32_bf16 v[116:119], v[196:199], v[240:243], v[116:119]
	ds_read_b128 v[196:199], v167 offset:8832
	s_waitcnt lgkmcnt(10)
	v_mfma_f32_16x16x32_bf16 v[124:127], v[200:203], v[244:247], v[124:127]
	ds_read_b128 v[200:203], v167 offset:13184
	s_waitcnt lgkmcnt(10)
	v_mfma_f32_16x16x32_bf16 v[120:123], v[204:207], v[244:247], v[120:123]
	ds_read_b128 v[204:207], v167 offset:17536
	s_waitcnt lgkmcnt(10)
	v_mfma_f32_16x16x32_bf16 v[112:115], v[208:211], v[244:247], v[112:115]
	ds_read_b128 v[208:211], v167 offset:21888
	s_waitcnt lgkmcnt(10)
	v_mfma_f32_16x16x32_bf16 v[108:111], v[168:171], v[244:247], v[108:111]
	ds_read_b128 v[168:171], v167 offset:26240
	s_waitcnt lgkmcnt(10)
	v_mfma_f32_16x16x32_bf16 v[104:107], v[172:175], v[244:247], v[104:107]
	ds_read_b128 v[172:175], v167 offset:30592
	s_waitcnt lgkmcnt(10)
	v_mfma_f32_16x16x32_bf16 v[100:103], v[176:179], v[244:247], v[100:103]
	ds_read_b128 v[176:179], v167 offset:192
	s_waitcnt lgkmcnt(10)
	v_mfma_f32_16x16x32_bf16 v[96:99], v[180:183], v[244:247], v[96:99]
	ds_read_b128 v[180:183], v167 offset:4544
	s_waitcnt lgkmcnt(10)
	v_mfma_f32_16x16x32_bf16 v[116:119], v[184:187], v[244:247], v[116:119]
	ds_read_b128 v[184:187], v167 offset:8896
	s_waitcnt lgkmcnt(10)
	v_mfma_f32_16x16x32_bf16 v[124:127], v[188:191], v[248:251], v[124:127]
	ds_read_b128 v[188:191], v167 offset:13248
	s_waitcnt lgkmcnt(10)
	v_mfma_f32_16x16x32_bf16 v[120:123], v[192:195], v[248:251], v[120:123]
	ds_read_b128 v[192:195], v167 offset:17600
	s_waitcnt lgkmcnt(10)
	v_mfma_f32_16x16x32_bf16 v[112:115], v[196:199], v[248:251], v[112:115]
	ds_read_b128 v[196:199], v167 offset:21952
	s_waitcnt lgkmcnt(10)
	v_mfma_f32_16x16x32_bf16 v[108:111], v[200:203], v[248:251], v[108:111]
	ds_read_b128 v[200:203], v167 offset:26304
	s_waitcnt lgkmcnt(10)
	v_mfma_f32_16x16x32_bf16 v[104:107], v[204:207], v[248:251], v[104:107]
	ds_read_b128 v[204:207], v167 offset:30656
	s_waitcnt lgkmcnt(10)
	v_mfma_f32_16x16x32_bf16 v[100:103], v[208:211], v[248:251], v[100:103]
	s_waitcnt lgkmcnt(9)
	v_mfma_f32_16x16x32_bf16 v[96:99], v[168:171], v[248:251], v[96:99]
	s_waitcnt lgkmcnt(8)
	v_mfma_f32_16x16x32_bf16 v[212:215], v[172:175], v[248:251], v[116:119]
	s_waitcnt lgkmcnt(0)
	s_barrier
	s_waitcnt vmcnt(4)
	v_mfma_f32_16x16x32_bf16 v[124:127], v[176:179], v[252:255], v[124:127]
	v_mfma_f32_16x16x32_bf16 v[120:123], v[180:183], v[252:255], v[120:123]
	v_mfma_f32_16x16x32_bf16 v[116:119], v[184:187], v[252:255], v[112:115]
	v_mfma_f32_16x16x32_bf16 v[112:115], v[188:191], v[252:255], v[108:111]
	v_mfma_f32_16x16x32_bf16 v[108:111], v[192:195], v[252:255], v[104:107]
	v_mfma_f32_16x16x32_bf16 v[104:107], v[196:199], v[252:255], v[100:103]
	v_mfma_f32_16x16x32_bf16 v[100:103], v[200:203], v[252:255], v[96:99]
	v_mfma_f32_16x16x32_bf16 v[96:99], v[204:207], v[252:255], v[212:215]
	s_and_b64 vcc, exec, s[8:9]
	s_cbranch_vccz .LBB0_405
	s_and_saveexec_b64 s[8:9], s[6:7]
	s_xor_b64 s[8:9], exec, s[8:9]
	s_or_b32 s24, s24, 1
	s_sub_i32 s25, 33, s24
	s_or_saveexec_b64 s[8:9], s[8:9]
	v_mov_b32_e32 v136, s25
	s_xor_b64 exec, exec, s[8:9]
	s_add_i32 s24, s3, -1
	v_mov_b32_e32 v136, s24
	s_or_b64 exec, exec, s[8:9]
	s_add_i32 s8, s3, 1
	s_cbranch_execnz .LBB0_400
